# combination: v2 + hgrn interval-2 pipelining + hgrn counted waits + peeled first K-iteration in in-proj/mlp-up GEMMs
# speedup vs baseline: 1.0121x; 1.0121x over previous
.LBB0_508:
	v_add_u32_e32 v109, v72, v64
	v_add_u32_e32 v108, v73, v64
	ds_read_b64_tr_b16 v[40:41], v104 offset:27648
	ds_read_b64_tr_b16 v[42:43], v104 offset:28224
	v_exp_f32_e32 v60, v118
	v_exp_f32_e32 v61, v119
	ds_read_b128 v[44:47], v109 offset:36864
	v_exp_f32_e32 v62, v120
	v_exp_f32_e32 v63, v121
	ds_read_b128 v[36:39], v108 offset:36864
	s_waitcnt lgkmcnt(1)
	v_mfma_f32_16x16x32_bf16 v[44:47], v[40:43], v[44:47], 0
	ds_read_b64_tr_b16 v[48:49], v104 offset:18432
	ds_read_b64_tr_b16 v[50:51], v104 offset:19008
	ds_read_b64_tr_b16 v[52:53], v104 offset:32256
	v_pk_mul_f32 v[30:31], v[30:31], v[62:63]
	v_pk_mul_f32 v[28:29], v[28:29], v[60:61]
	s_waitcnt lgkmcnt(3)
	v_mfma_f32_16x16x32_bf16 v[36:39], v[40:43], v[36:39], 0
	ds_read_b64_tr_b16 v[40:41], v106 offset:27648
	ds_read_b64_tr_b16 v[42:43], v106 offset:28224
	ds_read_b64_tr_b16 v[56:57], v107 offset:27648
	ds_read_b64_tr_b16 v[58:59], v107 offset:28224
	ds_read_b64_tr_b16 v[54:55], v104 offset:32832
	v_pk_mul_f32 v[34:35], v[34:35], v[62:63]
	v_pk_mul_f32 v[32:33], v[32:33], v[60:61]
	s_waitcnt lgkmcnt(3)
	v_mfma_f32_16x16x32_bf16 v[28:31], v[48:51], v[40:43], v[28:31]
	v_add_u32_e32 v113, v72, v74
	v_add_u32_e32 v112, v73, v74
	v_readlane_b32 s4, v255, 10
	s_waitcnt lgkmcnt(1)
	v_mfma_f32_16x16x32_bf16 v[40:43], v[48:51], v[56:59], v[32:35]
	s_nop 2
	ds_read_b128 v[32:35], v109 offset:36928
	ds_read_b64_tr_b16 v[48:49], v104 offset:23616
	ds_read_b128 v[56:59], v108 offset:36928
	s_and_b64 vcc, exec, s[34:35]
	s_waitcnt lgkmcnt(2)
	v_mfma_f32_16x16x32_bf16 v[60:63], v[52:55], v[32:35], v[44:47]
	s_nop 2
	ds_read_b64_tr_b16 v[46:47], v104 offset:23040
	ds_read_b64_tr_b16 v[32:33], v106 offset:32256
	s_waitcnt lgkmcnt(2)
	v_mfma_f32_16x16x32_bf16 v[36:39], v[52:55], v[56:59], v[36:39]
	ds_read_b64_tr_b16 v[34:35], v106 offset:32832
	ds_read_b64_tr_b16 v[50:51], v107 offset:32256
	ds_read_b64_tr_b16 v[52:53], v107 offset:32832
	ds_read_b128 v[54:57], v105 offset:46080
	s_waitcnt lgkmcnt(3)
	v_mfma_f32_16x16x32_bf16 v[32:35], v[46:49], v[32:35], v[28:31]
	s_waitcnt lgkmcnt(1)
	v_mfma_f32_16x16x32_bf16 v[28:31], v[46:49], v[50:53], v[40:43]
	s_nop 2
	ds_read_b128 v[40:43], v109 offset:9216
	ds_read_b128 v[44:47], v108 offset:9216
	ds_read_b128 v[48:51], v105 offset:46144
	s_waitcnt lgkmcnt(1)
	v_mfma_f32_16x16x32_bf16 v[36:39], v[54:57], v[44:47], v[36:39]
	ds_read_b128 v[44:47], v109 offset:9280
	v_mfma_f32_16x16x32_bf16 v[40:43], v[54:57], v[40:43], v[60:63]
	s_waitcnt lgkmcnt(0)
	v_mfma_f32_16x16x32_bf16 v[40:43], v[48:51], v[44:47], v[40:43]
	ds_read_b128 v[44:47], v108 offset:9280
	s_waitcnt lgkmcnt(0)
	v_mfma_f32_16x16x32_bf16 v[36:39], v[48:51], v[44:47], v[36:39]
	v_cvt_pk_bf16_f32 v44, v32, v33
	v_cvt_pk_bf16_f32 v45, v34, v35
	ds_write_b64 v113, v[44:45] offset:55296
	v_cvt_pk_bf16_f32 v44, v28, v29
	v_cvt_pk_bf16_f32 v45, v30, v31
	ds_write_b64 v112, v[44:45] offset:55296
	v_add_u32_e32 v44, s48, v75
	v_lshl_or_b32 v180, v44, 10, v76
	v_cvt_pk_bf16_f32 v40, v40, v41
	v_cvt_pk_bf16_f32 v41, v42, v43
	v_lshl_add_u64 v[42:43], v[180:181], 1, s[92:93]
	global_store_dwordx2 v[42:43], v[40:41], off
	v_add_u32_e32 v40, s48, v77
	v_lshl_or_b32 v180, v40, 10, v76
	v_cvt_pk_bf16_f32 v36, v36, v37
	v_cvt_pk_bf16_f32 v37, v38, v39
	v_lshl_add_u64 v[38:39], v[180:181], 1, s[92:93]
	global_store_dwordx2 v[38:39], v[36:37], off
	v_mov_b32_e32 v36, v68
	s_waitcnt lgkmcnt(0)
	s_barrier
	v_mov_b32_e32 v43, 0
	v_lshrrev_b32_e32 v37, 3, v36
	v_and_or_b32 v40, v37, 7, s70
	v_and_b32_e32 v41, 7, v36
	v_lshlrev_b32_e32 v36, 8, v40
	v_lshlrev_b32_e32 v37, 5, v41
	v_add3_u32 v36, s4, v36, v37
	ds_read_b128 v[44:47], v36
	ds_read_b128 v[36:39], v36 offset:16
	v_mul_lo_u32 v116, v40, s72
	v_lshlrev_b32_e32 v117, 4, v41
	v_lshlrev_b32_e32 v115, 3, v41
	v_add3_u32 v114, 0, v116, v117
	v_mov_b32_e32 v42, 0
	v_mov_b32_e32 v41, 0
	v_mov_b32_e32 v40, 0
	v_mov_b32_e32 v51, 0
	v_mov_b32_e32 v50, 0
	v_mov_b32_e32 v49, 0
	v_mov_b32_e32 v48, 0
	s_waitcnt vmcnt(7)
	ds_write_b128 v114, v[24:27] offset:27648
	s_cbranch_vccnz .LBB0_510
	v_lshl_add_u32 v40, v115, 2, s62
	ds_read_b128 v[48:51], v40
	ds_read_b128 v[40:43], v40 offset:16
